# attention loop: pre-barrier SALU hoist, back-edge rotation, MFMA-first segment head, group-asymmetric LDS-DMA issue point (waves0-3 after 4 QK MFMAs, waves4-7 at head)
# speedup vs baseline: 1.0082x; 1.0082x over previous
; __device__ __forceinline__ void partialSM(f32x16& p0, f32x16& p1, float& m_ref, float& alpha, bool first) {
;   constexpr float THRL = THR * 1.4426950408889634f;
;   float pmax = p0[0];
; #pragma unroll
;   for (int r = 1; r < 16; ++r) pmax = fmaxf(pmax, p0[r]);
; #pragma unroll
;   for (int r = 0; r < 16; ++r) pmax = fmaxf(pmax, p1[r]);
;   { auto rr = __builtin_amdgcn_permlane32_swap(__float_as_uint(pmax), __float_as_uint(pmax), false, false);
;     pmax = fmaxf(__uint_as_float(rr[0]), __uint_as_float(rr[1])); }
;   if (__builtin_expect(!first && __all(pmax <= THRL), 1)) { alpha = 1.f; }
;   else { const float dl = first ? pmax : fmaxf(pmax, 0.f); m_ref += dl; alpha = first ? 1.f : __builtin_amdgcn_exp2f(-dl);
; #pragma unroll
;     for (int r = 0; r < 16; ++r) { p0[r] -= dl; p1[r] -= dl; } }
; #pragma unroll
;   for (int r = 0; r < 16; ++r) p0[r] = __builtin_amdgcn_exp2f(p0[r]);
; }
; __device__ __forceinline__ void finishSM(f32x16& p0, f32x16& p1, float alpha, float& l_reg, bf16x8& pa0, bf16x8& pa1, bf16x8& pa2, bf16x8& pa3) {
; #pragma unroll
;   for (int r = 0; r < 16; ++r) p1[r] = __builtin_amdgcn_exp2f(p1[r]);
;   float ps = 0;
; #pragma unroll
;   for (int r = 0; r < 16; ++r) ps += p0[r];
; #pragma unroll
;   for (int r = 0; r < 16; ++r) ps += p1[r];
;   { auto rr = __builtin_amdgcn_permlane32_swap(__float_as_uint(ps), __float_as_uint(ps), false, false);
;     ps = __uint_as_float(rr[0]) + __uint_as_float(rr[1]); }
;   l_reg = l_reg * alpha + ps;
;     ...
;   PK4(p0, 0, pa0); PK4(p0, 8, pa1); PK4(p1, 0, pa2); PK4(p1, 8, pa3);
;     ...
; }
; __device__ __forceinline__ void qkt(f32x16& p0, f32x16& p1, const char* Ks, const bf16x8* qr, int r32, int hi, float m_ref) {
; #pragma unroll
;   for (int r = 0; r < 16; ++r) { p0[r] = -m_ref; p1[r] = -m_ref; }
; __device__ __forceinline__ void attn_unit(const bf16_t* __restrict__ Qb, const bf16_t* __restrict__ Kh, const bf16_t* __restrict__ Vh, int seq, char* lds,
;                                           int mode, float* scratch, float lam, float gscale, const float* __restrict__ subg, bf16_t* outp) {
;     ...
;   for (int j = 1; j + 1 < NT; j += 2) {
;     SBAR(); qkt(pB0, pB1, K_lds + bc * SHM_K, qr, r32, hi, m_reg);
;     finishSM(pA0, pA1, alA, l_reg, pa0, pa1, pa2, pa3); SBAR();
;     SLOAD(SO, (j + 2) * KVBLK); SBAR();
;     pv_d0(o, vb0 + bp * SHM_V, pa0, pa1, pa2, pa3); partialSM(pB0, pB1, m_reg, alB, false);
.Lat_noprio:
	s_waitcnt lgkmcnt(0)
	v_xor_b32_e32 v128, 0x80000000, v181
	v_mov_b32_e32 v129, v128
	v_mov_b32_e32 v130, v128
	v_mov_b32_e32 v131, v128
	v_mov_b32_e32 v132, v128
	v_mov_b32_e32 v133, v128
	v_mov_b32_e32 v134, v128
	v_mov_b32_e32 v135, v128
	v_mov_b32_e32 v136, v128
	v_mov_b32_e32 v137, v128
	v_mov_b32_e32 v138, v128
	v_mov_b32_e32 v139, v128
	v_mov_b32_e32 v140, v128
	v_mov_b32_e32 v141, v128
	v_mov_b32_e32 v142, v128
	v_mov_b32_e32 v143, v128
	s_barrier
	s_mov_b32 s58, 0x2000
	v_add_u32_e32 v218, s58, v173
	ds_read_b128 v[182:185], v218 offset:49152
	ds_read_b128 v[186:189], v218 offset:53248
	v_add_u32_e32 v218, s58, v175
	ds_read_b128 v[190:193], v218 offset:49152
	ds_read_b128 v[194:197], v218 offset:53248
	v_add_u32_e32 v218, s58, v174
	ds_read_b128 v[198:201], v218 offset:49152
	ds_read_b128 v[202:205], v218 offset:53248
	v_add_u32_e32 v218, s58, v176
	ds_read_b128 v[206:209], v218 offset:49152
	ds_read_b128 v[210:213], v218 offset:53248
	s_mov_b32 s21, 0
	s_lshl_b32 s59, s2, 14
	v_add_u32_e32 v172, s59, v177
	s_lshl_b32 s20, s0, 14
	s_add_i32 s20, s20, s79
	s_add_i32 s20, s20, s79
	s_add_i32 s58, s52, 3
	s_and_b32 s58, s58, 3
	s_lshl_b32 s58, s58, 13
	s_add_i32 s58, s58, s79
	s_add_i32 s58, s58, 0xc000
	v_readfirstlane_b32 s59, v214
	s_nop 3
	s_lshr_b32 s59, s59, 8
	s_cmp_eq_u32 s59, 1
	s_cbranch_scc1 .Lg1_loop
.Lat_loop:
	s_barrier
	s_waitcnt lgkmcnt(7)
	v_mfma_f32_32x32x16_bf16 v[96:111], v[182:185], v[124:127], v[128:143]
	ds_read_b64_tr_b16 v[182:183], v172 offset:0x0
	ds_read_b64_tr_b16 v[184:185], v172 offset:0x800
	v_add_f32_e32 v159, v64, v65
	v_cvt_pk_bf16_f32 v64, v64, v65
	v_add_f32_e32 v160, v66, v67
	v_cvt_pk_bf16_f32 v65, v66, v67
	v_add_f32_e32 v159, v68, v159
	v_add_f32_e32 v160, v69, v160
	v_cvt_pk_bf16_f32 v66, v68, v69
	s_waitcnt lgkmcnt(8)
	v_mfma_f32_32x32x16_bf16 v[236:251], v[186:189], v[124:127], v[128:143]
	ds_read_b64_tr_b16 v[186:187], v172 offset:0x1000
	ds_read_b64_tr_b16 v[188:189], v172 offset:0x1800
	v_add_f32_e32 v159, v70, v159
	v_add_f32_e32 v160, v71, v160
	v_cvt_pk_bf16_f32 v67, v70, v71
	v_add_f32_e32 v159, v72, v159
	v_add_f32_e32 v160, v73, v160
	v_cvt_pk_bf16_f32 v68, v72, v73
	v_add_f32_e32 v159, v74, v159
	s_waitcnt lgkmcnt(9)
	v_mfma_f32_32x32x16_bf16 v[96:111], v[190:193], v[120:123], v[96:111]
	ds_read_b64_tr_b16 v[190:191], v172 offset:0x2000
	ds_read_b64_tr_b16 v[192:193], v172 offset:0x2800
	v_add_f32_e32 v160, v75, v160
	v_cvt_pk_bf16_f32 v69, v74, v75
	v_add_f32_e32 v159, v76, v159
	v_add_f32_e32 v160, v77, v160
	v_cvt_pk_bf16_f32 v70, v76, v77
	v_add_f32_e32 v159, v78, v159
	v_add_f32_e32 v160, v79, v160
	s_waitcnt lgkmcnt(10)
	v_mfma_f32_32x32x16_bf16 v[236:251], v[194:197], v[120:123], v[236:251]
	ds_read_b64_tr_b16 v[194:195], v172 offset:0x3000
	ds_read_b64_tr_b16 v[196:197], v172 offset:0x3800
	s_mov_b32 m0, s20
	s_nop 0
	global_load_lds_dwordx4 v233, s[24:25]
	s_add_i32 m0, m0, 0x400
	s_nop 0
	global_load_lds_dwordx4 v234, s[24:25]
	s_mov_b32 m0, s58
	s_nop 0
	global_load_lds_dwordx4 v232, s[24:25]
	s_add_u32 s24, s24, 0x10000
	s_addc_u32 s25, s25, 0
	v_cvt_pk_bf16_f32 v71, v78, v79
	v_add_f32_e32 v159, v80, v159
	v_add_f32_e32 v160, v81, v160
	v_cvt_pk_bf16_f32 v72, v80, v81
	v_add_f32_e32 v159, v82, v159
	v_add_f32_e32 v160, v83, v160
	v_cvt_pk_bf16_f32 v73, v82, v83
	s_waitcnt lgkmcnt(11)
	v_mfma_f32_32x32x16_bf16 v[96:111], v[198:201], v[116:119], v[96:111]
	ds_read_b64_tr_b16 v[198:199], v172 offset:0x200
	ds_read_b64_tr_b16 v[200:201], v172 offset:0xa00
	v_add_f32_e32 v159, v84, v159
	v_add_f32_e32 v160, v85, v160
	v_cvt_pk_bf16_f32 v74, v84, v85
	v_add_f32_e32 v159, v86, v159
	v_add_f32_e32 v160, v87, v160
	v_cvt_pk_bf16_f32 v75, v86, v87
	v_add_f32_e32 v159, v88, v159
	s_waitcnt lgkmcnt(12)
	v_mfma_f32_32x32x16_bf16 v[236:251], v[202:205], v[116:119], v[236:251]
	ds_read_b64_tr_b16 v[202:203], v172 offset:0x1200
	ds_read_b64_tr_b16 v[204:205], v172 offset:0x1a00
	v_add_f32_e32 v160, v89, v160
	v_cvt_pk_bf16_f32 v76, v88, v89
	v_add_f32_e32 v159, v90, v159
	v_add_f32_e32 v160, v91, v160
	v_cvt_pk_bf16_f32 v77, v90, v91
	v_add_f32_e32 v159, v92, v159
	v_add_f32_e32 v160, v93, v160
	s_waitcnt lgkmcnt(13)
	v_mfma_f32_32x32x16_bf16 v[96:111], v[206:209], v[112:115], v[96:111]
	ds_read_b64_tr_b16 v[206:207], v172 offset:0x2200
	ds_read_b64_tr_b16 v[208:209], v172 offset:0x2a00
	v_cvt_pk_bf16_f32 v78, v92, v93
	v_add_f32_e32 v159, v94, v159
	v_add_f32_e32 v160, v95, v160
	v_cvt_pk_bf16_f32 v79, v94, v95
	v_add_f32_e32 v159, v159, v160
	v_fma_f32 v167, v167, v235, v159
	s_waitcnt lgkmcnt(14)
	v_mfma_f32_32x32x16_bf16 v[236:251], v[210:213], v[112:115], v[236:251]
	s_waitcnt lgkmcnt(12)
	v_mfma_f32_32x32x16_bf16 v[0:15], v[64:67], v[182:185], v[0:15]
	ds_read_b64_tr_b16 v[210:211], v172 offset:0x3200
	ds_read_b64_tr_b16 v[212:213], v172 offset:0x3a00
	v_max3_f32 v161, v96, v97, v98
	v_max3_f32 v161, v161, v99, v100
	v_max3_f32 v161, v161, v101, v102
	v_max3_f32 v161, v161, v103, v104
	s_waitcnt lgkmcnt(12)
	v_mfma_f32_32x32x16_bf16 v[0:15], v[68:71], v[186:189], v[0:15]
	ds_read_b64_tr_b16 v[182:183], v172 offset:0x400
	ds_read_b64_tr_b16 v[184:185], v172 offset:0xc00
	v_max3_f32 v161, v161, v105, v106
	v_max3_f32 v161, v161, v107, v108
	v_max3_f32 v161, v161, v109, v110
	v_max_f32_e32 v161, v161, v111
	s_waitcnt lgkmcnt(12)
	v_mfma_f32_32x32x16_bf16 v[0:15], v[72:75], v[190:193], v[0:15]
	ds_read_b64_tr_b16 v[186:187], v172 offset:0x1400
	ds_read_b64_tr_b16 v[188:189], v172 offset:0x1c00
	v_max3_f32 v216, v236, v237, v238
	v_max3_f32 v216, v216, v239, v240
	v_max3_f32 v216, v216, v241, v242
	v_max3_f32 v216, v216, v243, v244
	s_waitcnt lgkmcnt(12)
	v_mfma_f32_32x32x16_bf16 v[0:15], v[76:79], v[194:197], v[0:15]
	ds_read_b64_tr_b16 v[190:191], v172 offset:0x2400
	ds_read_b64_tr_b16 v[192:193], v172 offset:0x2c00
	v_max3_f32 v216, v216, v245, v246
	v_max3_f32 v216, v216, v247, v248
	v_max3_f32 v216, v216, v249, v250
	v_max_f32_e32 v216, v216, v251
	v_max_f32_e32 v161, v161, v216
	v_cmp_ge_f32_e32 vcc, s66, v161
	s_cmp_eq_u64 vcc, exec
	s_cbranch_scc0 .Lat_rare0
	v_mov_b32_e32 v158, 1.0

; __device__ __forceinline__ void partialSM(f32x16& p0, f32x16& p1, float& m_ref, float& alpha, bool first) {
;   constexpr float THRL = THR * 1.4426950408889634f;
;   float pmax = p0[0];
; #pragma unroll
;   for (int r = 1; r < 16; ++r) pmax = fmaxf(pmax, p0[r]);
; #pragma unroll
;   for (int r = 0; r < 16; ++r) pmax = fmaxf(pmax, p1[r]);
;   { auto rr = __builtin_amdgcn_permlane32_swap(__float_as_uint(pmax), __float_as_uint(pmax), false, false);
;     pmax = fmaxf(__uint_as_float(rr[0]), __uint_as_float(rr[1])); }
;   if (__builtin_expect(!first && __all(pmax <= THRL), 1)) { alpha = 1.f; }
;   else { const float dl = first ? pmax : fmaxf(pmax, 0.f); m_ref += dl; alpha = first ? 1.f : __builtin_amdgcn_exp2f(-dl);
; #pragma unroll
;     for (int r = 0; r < 16; ++r) { p0[r] -= dl; p1[r] -= dl; } }
; #pragma unroll
;   for (int r = 0; r < 16; ++r) p0[r] = __builtin_amdgcn_exp2f(p0[r]);
; }
; __device__ __forceinline__ void finishSM(f32x16& p0, f32x16& p1, float alpha, float& l_reg, bf16x8& pa0, bf16x8& pa1, bf16x8& pa2, bf16x8& pa3) {
; #pragma unroll
;   for (int r = 0; r < 16; ++r) p1[r] = __builtin_amdgcn_exp2f(p1[r]);
;   float ps = 0;
; #pragma unroll
;   for (int r = 0; r < 16; ++r) ps += p0[r];
; #pragma unroll
;   for (int r = 0; r < 16; ++r) ps += p1[r];
;   { auto rr = __builtin_amdgcn_permlane32_swap(__float_as_uint(ps), __float_as_uint(ps), false, false);
;     ps = __uint_as_float(rr[0]) + __uint_as_float(rr[1]); }
;   l_reg = l_reg * alpha + ps;
;     ...
;   PK4(p0, 0, pa0); PK4(p0, 8, pa1); PK4(p1, 0, pa2); PK4(p1, 8, pa3);
;     ...
; }
; __device__ __forceinline__ void qkt(f32x16& p0, f32x16& p1, const char* Ks, const bf16x8* qr, int r32, int hi, float m_ref) {
; #pragma unroll
;   for (int r = 0; r < 16; ++r) { p0[r] = -m_ref; p1[r] = -m_ref; }
; #pragma unroll
; __device__ __forceinline__ void attn_unit(const bf16_t* __restrict__ Qb, const bf16_t* __restrict__ Kh, const bf16_t* __restrict__ Vh, int seq, char* lds,
;                                           int mode, float* scratch, float lam, float gscale, const float* __restrict__ subg, bf16_t* outp) {
;     ...
;     SBAR(); qkt(pA0, pA1, K_lds + bc * SHM_K, qr, r32, hi, m_reg);
;     finishSM(pB0, pB1, alB, l_reg, pa0, pa1, pa2, pa3); SBAR();
;     if (j + 3 < NT) SLOAD(SE, (j + 3) * KVBLK); SBAR();
;     pv_d0(o, vb0 + bp * SHM_V, pa0, pa1, pa2, pa3); partialSM(pA0, pA1, m_reg, alA, false);
.Lat_rescback0:
	s_mov_b32 s21, 0
	s_lshl_b32 s59, s1, 14
	v_add_u32_e32 v172, s59, v177
	s_lshl_b32 s20, s2, 14
	s_add_i32 s20, s20, s79
	s_add_i32 s20, s20, s79
	s_add_i32 s58, s52, 4
	s_and_b32 s58, s58, 3
	s_lshl_b32 s58, s58, 13
	s_add_i32 s58, s58, s79
	s_add_i32 s58, s58, 0xc000
	s_waitcnt vmcnt(3)
	s_barrier
	s_waitcnt lgkmcnt(7)
	v_mfma_f32_32x32x16_bf16 v[64:79], v[182:185], v[124:127], v[128:143]
	ds_read_b64_tr_b16 v[182:183], v172 offset:0x0
	ds_read_b64_tr_b16 v[184:185], v172 offset:0x800
	v_add_f32_e32 v159, v96, v97
	v_cvt_pk_bf16_f32 v96, v96, v97
	v_add_f32_e32 v160, v98, v99
	v_cvt_pk_bf16_f32 v97, v98, v99
	v_add_f32_e32 v159, v100, v159
	v_add_f32_e32 v160, v101, v160
	v_cvt_pk_bf16_f32 v98, v100, v101
	s_waitcnt lgkmcnt(8)
	v_mfma_f32_32x32x16_bf16 v[80:95], v[186:189], v[124:127], v[128:143]
	ds_read_b64_tr_b16 v[186:187], v172 offset:0x1000
	ds_read_b64_tr_b16 v[188:189], v172 offset:0x1800
	v_add_f32_e32 v159, v102, v159
	v_add_f32_e32 v160, v103, v160
	v_cvt_pk_bf16_f32 v99, v102, v103
	v_add_f32_e32 v159, v104, v159
	v_add_f32_e32 v160, v105, v160
	v_cvt_pk_bf16_f32 v100, v104, v105
	v_add_f32_e32 v159, v106, v159
	s_waitcnt lgkmcnt(9)
	v_mfma_f32_32x32x16_bf16 v[64:79], v[190:193], v[120:123], v[64:79]
	ds_read_b64_tr_b16 v[190:191], v172 offset:0x2000
	ds_read_b64_tr_b16 v[192:193], v172 offset:0x2800
	v_add_f32_e32 v160, v107, v160
	v_cvt_pk_bf16_f32 v101, v106, v107
	v_add_f32_e32 v159, v108, v159
	v_add_f32_e32 v160, v109, v160
	v_cvt_pk_bf16_f32 v102, v108, v109
	v_add_f32_e32 v159, v110, v159
	v_add_f32_e32 v160, v111, v160
	s_waitcnt lgkmcnt(10)
	v_mfma_f32_32x32x16_bf16 v[80:95], v[194:197], v[120:123], v[80:95]
	ds_read_b64_tr_b16 v[194:195], v172 offset:0x3000
	ds_read_b64_tr_b16 v[196:197], v172 offset:0x3800
	s_mov_b32 m0, s20
	s_nop 0
	global_load_lds_dwordx4 v233, s[24:25]
	s_add_i32 m0, m0, 0x400
	s_nop 0
	global_load_lds_dwordx4 v234, s[24:25]
	s_mov_b32 m0, s58
	s_nop 0
	global_load_lds_dwordx4 v232, s[24:25]
	s_add_u32 s24, s24, 0x10000
	s_addc_u32 s25, s25, 0
	v_cvt_pk_bf16_f32 v103, v110, v111
	v_add_f32_e32 v159, v236, v159
	v_add_f32_e32 v160, v237, v160
	v_cvt_pk_bf16_f32 v104, v236, v237
	v_add_f32_e32 v159, v238, v159
	v_add_f32_e32 v160, v239, v160
	v_cvt_pk_bf16_f32 v105, v238, v239
	s_waitcnt lgkmcnt(11)
	v_mfma_f32_32x32x16_bf16 v[64:79], v[198:201], v[116:119], v[64:79]
	ds_read_b64_tr_b16 v[198:199], v172 offset:0x200
	ds_read_b64_tr_b16 v[200:201], v172 offset:0xa00
	v_add_f32_e32 v159, v240, v159
	v_add_f32_e32 v160, v241, v160
	v_cvt_pk_bf16_f32 v106, v240, v241
	v_add_f32_e32 v159, v242, v159
	v_add_f32_e32 v160, v243, v160
	v_cvt_pk_bf16_f32 v107, v242, v243
	v_add_f32_e32 v159, v244, v159
	s_waitcnt lgkmcnt(12)
	v_mfma_f32_32x32x16_bf16 v[80:95], v[202:205], v[116:119], v[80:95]
	ds_read_b64_tr_b16 v[202:203], v172 offset:0x1200
	ds_read_b64_tr_b16 v[204:205], v172 offset:0x1a00
	v_add_f32_e32 v160, v245, v160
	v_cvt_pk_bf16_f32 v108, v244, v245
	v_add_f32_e32 v159, v246, v159
	v_add_f32_e32 v160, v247, v160
	v_cvt_pk_bf16_f32 v109, v246, v247
	v_add_f32_e32 v159, v248, v159
	v_add_f32_e32 v160, v249, v160
	s_waitcnt lgkmcnt(13)
	v_mfma_f32_32x32x16_bf16 v[64:79], v[206:209], v[112:115], v[64:79]
	ds_read_b64_tr_b16 v[206:207], v172 offset:0x2200
	ds_read_b64_tr_b16 v[208:209], v172 offset:0x2a00
	v_cvt_pk_bf16_f32 v110, v248, v249
	v_add_f32_e32 v159, v250, v159
	v_add_f32_e32 v160, v251, v160
	v_cvt_pk_bf16_f32 v111, v250, v251
	v_add_f32_e32 v159, v159, v160
	v_fma_f32 v167, v167, v158, v159
	s_waitcnt lgkmcnt(14)
	v_mfma_f32_32x32x16_bf16 v[80:95], v[210:213], v[112:115], v[80:95]
	s_waitcnt lgkmcnt(12)
	v_mfma_f32_32x32x16_bf16 v[0:15], v[96:99], v[182:185], v[0:15]
	ds_read_b64_tr_b16 v[210:211], v172 offset:0x3200
	ds_read_b64_tr_b16 v[212:213], v172 offset:0x3a00
	v_max3_f32 v161, v64, v65, v66
	v_max3_f32 v161, v161, v67, v68
	v_max3_f32 v161, v161, v69, v70
	v_max3_f32 v161, v161, v71, v72
	s_waitcnt lgkmcnt(12)
	v_mfma_f32_32x32x16_bf16 v[0:15], v[100:103], v[186:189], v[0:15]
	ds_read_b64_tr_b16 v[182:183], v172 offset:0x400
	ds_read_b64_tr_b16 v[184:185], v172 offset:0xc00
	v_max3_f32 v161, v161, v73, v74
	v_max3_f32 v161, v161, v75, v76
	v_max3_f32 v161, v161, v77, v78
	v_max_f32_e32 v161, v161, v79
	s_waitcnt lgkmcnt(12)
	v_mfma_f32_32x32x16_bf16 v[0:15], v[104:107], v[190:193], v[0:15]
	ds_read_b64_tr_b16 v[186:187], v172 offset:0x1400
	ds_read_b64_tr_b16 v[188:189], v172 offset:0x1c00
	v_max3_f32 v216, v80, v81, v82
	v_max3_f32 v216, v216, v83, v84
	v_max3_f32 v216, v216, v85, v86
	v_max3_f32 v216, v216, v87, v88
	s_waitcnt lgkmcnt(12)
	v_mfma_f32_32x32x16_bf16 v[0:15], v[108:111], v[194:197], v[0:15]
	ds_read_b64_tr_b16 v[190:191], v172 offset:0x2400
	ds_read_b64_tr_b16 v[192:193], v172 offset:0x2c00
	v_max3_f32 v216, v216, v89, v90
	v_max3_f32 v216, v216, v91, v92
	v_max3_f32 v216, v216, v93, v94
	v_max_f32_e32 v216, v216, v95
	v_max_f32_e32 v161, v161, v216
	v_cmp_ge_f32_e32 vcc, s66, v161
	s_cmp_eq_u64 vcc, exec
	s_cbranch_scc0 .Lat_rare1
	v_mov_b32_e32 v235, 1.0

; #define SBAR() __builtin_amdgcn_sched_barrier(0)
; #define SLOAD(i, k0) do { sr_[i].vs0 = *reinterpret_cast<const bf16x8*>(&Vh[(long)((k0) + sr) * LDQ + sc]); sr_[i].vs1 = *reinterpret_cast<const bf16x8*>(&Vh[(long)((k0) + 32 + sr) * LDQ + sc]); \
;     sr_[i].ks0 = *reinterpret_cast<const bf16x8*>(&Kh[(long)((k0) + kr) * LDQ + kc]); } while (0)
; #define SWRITE(b, i) do { *(bf16x8*)(V_lds + (b) * SHM_V + vst0) = sr_[i].vs0; *(bf16x8*)(V_lds + (b) * SHM_V + vst1) = sr_[i].vs1; \
;     *(bf16x8*)(K_lds + (b) * SHM_K + kst) = sr_[i].ks0; } while (0)
; #define SWAIT() asm volatile("s_waitcnt vmcnt(3)" ::: "memory")
; #define RESC(a) do { if (__any((a) < 1.f)) { if (hi == 0) al_l[r32] = (a); asm volatile("s_waitcnt lgkmcnt(0)" ::: "memory"); \
;     _Pragma("unroll") for (int d = 0; d < 4; ++d) _Pragma("unroll") for (int r = 0; r < 16; ++r) o[d][r] *= al_l[crow(r, hi)]; } } while (0)
; #define ROT3() do { const int t_ = bp; bp = bc; bc = bn; bn = t_; } while (0)
; __device__ __forceinline__ void attn_unit(const bf16_t* __restrict__ Qb, const bf16_t* __restrict__ Kh, const bf16_t* __restrict__ Vh, int seq, char* lds,
;                                           int mode, float* scratch, float lam, float gscale, const float* __restrict__ subg, bf16_t* outp) {
;     ...
;     RESC(alB); __syncthreads(); ROT3();
;     SBAR(); qkt(pA0, pA1, K_lds + bc * SHM_K, qr, r32, hi, m_reg);
;     finishSM(pB0, pB1, alB, l_reg, pa0, pa1, pa2, pa3); SBAR();
;     if (j + 3 < NT) SLOAD(SE, (j + 3) * KVBLK); SBAR();
;     pv_d0(o, vb0 + bp * SHM_V, pa0, pa1, pa2, pa3); partialSM(pA0, pA1, m_reg, alA, false);
;     SWAIT(); SWRITE(bn, SO);
;     RESC(alA); __syncthreads(); ROT3();
;   }
.Lat_rescback1:
	s_add_i32 s52, s52, 2
	s_cmpk_gt_u32 s52, 0xfe
	s_cbranch_scc1 .Lat_exit
	s_mov_b32 s58, s2
	s_mov_b32 s2, s0
	s_mov_b32 s0, s1
	s_mov_b32 s1, s58
	s_mov_b32 s21, 0
	s_lshl_b32 s59, s2, 14
	v_add_u32_e32 v172, s59, v177
	s_lshl_b32 s20, s0, 14
	s_add_i32 s20, s20, s79
	s_add_i32 s20, s20, s79
	s_add_i32 s58, s52, 3
	s_and_b32 s58, s58, 3
	s_lshl_b32 s58, s58, 13
	s_add_i32 s58, s58, s79
	s_add_i32 s58, s58, 0xc000
	s_waitcnt vmcnt(3)
	s_branch .Lat_loop

; __device__ __forceinline__ void partialSM(f32x16& p0, f32x16& p1, float& m_ref, float& alpha, bool first) {
;   constexpr float THRL = THR * 1.4426950408889634f;
;   float pmax = p0[0];
; #pragma unroll
;   for (int r = 1; r < 16; ++r) pmax = fmaxf(pmax, p0[r]);
; #pragma unroll
;   for (int r = 0; r < 16; ++r) pmax = fmaxf(pmax, p1[r]);
;   { auto rr = __builtin_amdgcn_permlane32_swap(__float_as_uint(pmax), __float_as_uint(pmax), false, false);
;     pmax = fmaxf(__uint_as_float(rr[0]), __uint_as_float(rr[1])); }
;   if (__builtin_expect(!first && __all(pmax <= THRL), 1)) { alpha = 1.f; }
;   else { const float dl = first ? pmax : fmaxf(pmax, 0.f); m_ref += dl; alpha = first ? 1.f : __builtin_amdgcn_exp2f(-dl);
; #pragma unroll
;     for (int r = 0; r < 16; ++r) { p0[r] -= dl; p1[r] -= dl; } }
; #pragma unroll
;   for (int r = 0; r < 16; ++r) p0[r] = __builtin_amdgcn_exp2f(p0[r]);
; }
; __device__ __forceinline__ void finishSM(f32x16& p0, f32x16& p1, float alpha, float& l_reg, bf16x8& pa0, bf16x8& pa1, bf16x8& pa2, bf16x8& pa3) {
; #pragma unroll
;   for (int r = 0; r < 16; ++r) p1[r] = __builtin_amdgcn_exp2f(p1[r]);
;   float ps = 0;
; #pragma unroll
;   for (int r = 0; r < 16; ++r) ps += p0[r];
; #pragma unroll
;   for (int r = 0; r < 16; ++r) ps += p1[r];
;   { auto rr = __builtin_amdgcn_permlane32_swap(__float_as_uint(ps), __float_as_uint(ps), false, false);
;     ps = __uint_as_float(rr[0]) + __uint_as_float(rr[1]); }
;   l_reg = l_reg * alpha + ps;
;     ...
;   PK4(p0, 0, pa0); PK4(p0, 8, pa1); PK4(p1, 0, pa2); PK4(p1, 8, pa3);
;     ...
; }
; __device__ __forceinline__ void qkt(f32x16& p0, f32x16& p1, const char* Ks, const bf16x8* qr, int r32, int hi, float m_ref) {
; #pragma unroll
;   for (int r = 0; r < 16; ++r) { p0[r] = -m_ref; p1[r] = -m_ref; }
; __device__ __forceinline__ void attn_unit(const bf16_t* __restrict__ Qb, const bf16_t* __restrict__ Kh, const bf16_t* __restrict__ Vh, int seq, char* lds,
;                                           int mode, float* scratch, float lam, float gscale, const float* __restrict__ subg, bf16_t* outp) {
;     ...
;   for (int j = 1; j + 1 < NT; j += 2) {
;     SBAR(); qkt(pB0, pB1, K_lds + bc * SHM_K, qr, r32, hi, m_reg);
;     finishSM(pA0, pA1, alA, l_reg, pa0, pa1, pa2, pa3); SBAR();
;     SLOAD(SO, (j + 2) * KVBLK); SBAR();
;     pv_d0(o, vb0 + bp * SHM_V, pa0, pa1, pa2, pa3); partialSM(pB0, pB1, m_reg, alB, false);
.Lg1_loop:
	s_barrier
	s_mov_b32 m0, s20
	s_nop 0
	global_load_lds_dwordx4 v233, s[24:25]
	s_add_i32 m0, m0, 0x400
	s_nop 0
	global_load_lds_dwordx4 v234, s[24:25]
	s_mov_b32 m0, s58
	s_nop 0
	global_load_lds_dwordx4 v232, s[24:25]
	s_add_u32 s24, s24, 0x10000
	s_addc_u32 s25, s25, 0
	s_waitcnt lgkmcnt(7)
	v_mfma_f32_32x32x16_bf16 v[96:111], v[182:185], v[124:127], v[128:143]
	ds_read_b64_tr_b16 v[182:183], v172 offset:0x0
	ds_read_b64_tr_b16 v[184:185], v172 offset:0x800
	v_add_f32_e32 v159, v64, v65
	v_cvt_pk_bf16_f32 v64, v64, v65
	v_add_f32_e32 v160, v66, v67
	v_cvt_pk_bf16_f32 v65, v66, v67
	v_add_f32_e32 v159, v68, v159
	v_add_f32_e32 v160, v69, v160
	v_cvt_pk_bf16_f32 v66, v68, v69
	s_waitcnt lgkmcnt(8)
	v_mfma_f32_32x32x16_bf16 v[236:251], v[186:189], v[124:127], v[128:143]
	ds_read_b64_tr_b16 v[186:187], v172 offset:0x1000
	ds_read_b64_tr_b16 v[188:189], v172 offset:0x1800
	v_add_f32_e32 v159, v70, v159
	v_add_f32_e32 v160, v71, v160
	v_cvt_pk_bf16_f32 v67, v70, v71
	v_add_f32_e32 v159, v72, v159
	v_add_f32_e32 v160, v73, v160
	v_cvt_pk_bf16_f32 v68, v72, v73
	v_add_f32_e32 v159, v74, v159
	s_waitcnt lgkmcnt(9)
	v_mfma_f32_32x32x16_bf16 v[96:111], v[190:193], v[120:123], v[96:111]
	ds_read_b64_tr_b16 v[190:191], v172 offset:0x2000
	ds_read_b64_tr_b16 v[192:193], v172 offset:0x2800
	v_add_f32_e32 v160, v75, v160
	v_cvt_pk_bf16_f32 v69, v74, v75
	v_add_f32_e32 v159, v76, v159
	v_add_f32_e32 v160, v77, v160
	v_cvt_pk_bf16_f32 v70, v76, v77
	v_add_f32_e32 v159, v78, v159
	v_add_f32_e32 v160, v79, v160
	s_waitcnt lgkmcnt(10)
	v_mfma_f32_32x32x16_bf16 v[236:251], v[194:197], v[120:123], v[236:251]
	ds_read_b64_tr_b16 v[194:195], v172 offset:0x3000
	ds_read_b64_tr_b16 v[196:197], v172 offset:0x3800
	v_cvt_pk_bf16_f32 v71, v78, v79
	v_add_f32_e32 v159, v80, v159
	v_add_f32_e32 v160, v81, v160
	v_cvt_pk_bf16_f32 v72, v80, v81
	v_add_f32_e32 v159, v82, v159
	v_add_f32_e32 v160, v83, v160
	v_cvt_pk_bf16_f32 v73, v82, v83
	s_waitcnt lgkmcnt(11)
	v_mfma_f32_32x32x16_bf16 v[96:111], v[198:201], v[116:119], v[96:111]
	ds_read_b64_tr_b16 v[198:199], v172 offset:0x200
	ds_read_b64_tr_b16 v[200:201], v172 offset:0xa00
	v_add_f32_e32 v159, v84, v159
	v_add_f32_e32 v160, v85, v160
	v_cvt_pk_bf16_f32 v74, v84, v85
	v_add_f32_e32 v159, v86, v159
	v_add_f32_e32 v160, v87, v160
	v_cvt_pk_bf16_f32 v75, v86, v87
	v_add_f32_e32 v159, v88, v159
	s_waitcnt lgkmcnt(12)
	v_mfma_f32_32x32x16_bf16 v[236:251], v[202:205], v[116:119], v[236:251]
	ds_read_b64_tr_b16 v[202:203], v172 offset:0x1200
	ds_read_b64_tr_b16 v[204:205], v172 offset:0x1a00
	v_add_f32_e32 v160, v89, v160
	v_cvt_pk_bf16_f32 v76, v88, v89
	v_add_f32_e32 v159, v90, v159
	v_add_f32_e32 v160, v91, v160
	v_cvt_pk_bf16_f32 v77, v90, v91
	v_add_f32_e32 v159, v92, v159
	v_add_f32_e32 v160, v93, v160
	s_waitcnt lgkmcnt(13)
	v_mfma_f32_32x32x16_bf16 v[96:111], v[206:209], v[112:115], v[96:111]
	ds_read_b64_tr_b16 v[206:207], v172 offset:0x2200
	ds_read_b64_tr_b16 v[208:209], v172 offset:0x2a00
	v_cvt_pk_bf16_f32 v78, v92, v93
	v_add_f32_e32 v159, v94, v159
	v_add_f32_e32 v160, v95, v160
	v_cvt_pk_bf16_f32 v79, v94, v95
	v_add_f32_e32 v159, v159, v160
	v_fma_f32 v167, v167, v235, v159
	s_waitcnt lgkmcnt(14)
	v_mfma_f32_32x32x16_bf16 v[236:251], v[210:213], v[112:115], v[236:251]
	s_waitcnt lgkmcnt(12)
	v_mfma_f32_32x32x16_bf16 v[0:15], v[64:67], v[182:185], v[0:15]
	ds_read_b64_tr_b16 v[210:211], v172 offset:0x3200
	ds_read_b64_tr_b16 v[212:213], v172 offset:0x3a00
	v_max3_f32 v161, v96, v97, v98
	v_max3_f32 v161, v161, v99, v100
	v_max3_f32 v161, v161, v101, v102
	v_max3_f32 v161, v161, v103, v104
	s_waitcnt lgkmcnt(12)
	v_mfma_f32_32x32x16_bf16 v[0:15], v[68:71], v[186:189], v[0:15]
	ds_read_b64_tr_b16 v[182:183], v172 offset:0x400
	ds_read_b64_tr_b16 v[184:185], v172 offset:0xc00
	v_max3_f32 v161, v161, v105, v106
	v_max3_f32 v161, v161, v107, v108
	v_max3_f32 v161, v161, v109, v110
	v_max_f32_e32 v161, v161, v111
	s_waitcnt lgkmcnt(12)
	v_mfma_f32_32x32x16_bf16 v[0:15], v[72:75], v[190:193], v[0:15]
	ds_read_b64_tr_b16 v[186:187], v172 offset:0x1400
	ds_read_b64_tr_b16 v[188:189], v172 offset:0x1c00
	v_max3_f32 v216, v236, v237, v238
	v_max3_f32 v216, v216, v239, v240
	v_max3_f32 v216, v216, v241, v242
	v_max3_f32 v216, v216, v243, v244
	s_waitcnt lgkmcnt(12)
	v_mfma_f32_32x32x16_bf16 v[0:15], v[76:79], v[194:197], v[0:15]
	ds_read_b64_tr_b16 v[190:191], v172 offset:0x2400
	ds_read_b64_tr_b16 v[192:193], v172 offset:0x2c00
	v_max3_f32 v216, v216, v245, v246
	v_max3_f32 v216, v216, v247, v248
	v_max3_f32 v216, v216, v249, v250
	v_max_f32_e32 v216, v216, v251
	v_max_f32_e32 v161, v161, v216
	v_cmp_ge_f32_e32 vcc, s66, v161
	s_cmp_eq_u64 vcc, exec
	s_cbranch_scc0 .Lg1_rare0
	v_mov_b32_e32 v158, 1.0

; __device__ __forceinline__ void partialSM(f32x16& p0, f32x16& p1, float& m_ref, float& alpha, bool first) {
;   constexpr float THRL = THR * 1.4426950408889634f;
;   float pmax = p0[0];
; #pragma unroll
;   for (int r = 1; r < 16; ++r) pmax = fmaxf(pmax, p0[r]);
; #pragma unroll
;   for (int r = 0; r < 16; ++r) pmax = fmaxf(pmax, p1[r]);
;   { auto rr = __builtin_amdgcn_permlane32_swap(__float_as_uint(pmax), __float_as_uint(pmax), false, false);
;     pmax = fmaxf(__uint_as_float(rr[0]), __uint_as_float(rr[1])); }
;   if (__builtin_expect(!first && __all(pmax <= THRL), 1)) { alpha = 1.f; }
;   else { const float dl = first ? pmax : fmaxf(pmax, 0.f); m_ref += dl; alpha = first ? 1.f : __builtin_amdgcn_exp2f(-dl);
; #pragma unroll
;     for (int r = 0; r < 16; ++r) { p0[r] -= dl; p1[r] -= dl; } }
; #pragma unroll
;   for (int r = 0; r < 16; ++r) p0[r] = __builtin_amdgcn_exp2f(p0[r]);
; }
; __device__ __forceinline__ void finishSM(f32x16& p0, f32x16& p1, float alpha, float& l_reg, bf16x8& pa0, bf16x8& pa1, bf16x8& pa2, bf16x8& pa3) {
; #pragma unroll
;   for (int r = 0; r < 16; ++r) p1[r] = __builtin_amdgcn_exp2f(p1[r]);
;   float ps = 0;
; #pragma unroll
;   for (int r = 0; r < 16; ++r) ps += p0[r];
; #pragma unroll
;   for (int r = 0; r < 16; ++r) ps += p1[r];
;   { auto rr = __builtin_amdgcn_permlane32_swap(__float_as_uint(ps), __float_as_uint(ps), false, false);
;     ps = __uint_as_float(rr[0]) + __uint_as_float(rr[1]); }
;   l_reg = l_reg * alpha + ps;
;     ...
;   PK4(p0, 0, pa0); PK4(p0, 8, pa1); PK4(p1, 0, pa2); PK4(p1, 8, pa3);
;     ...
; }
; __device__ __forceinline__ void qkt(f32x16& p0, f32x16& p1, const char* Ks, const bf16x8* qr, int r32, int hi, float m_ref) {
; #pragma unroll
;   for (int r = 0; r < 16; ++r) { p0[r] = -m_ref; p1[r] = -m_ref; }
; #pragma unroll
; __device__ __forceinline__ void attn_unit(const bf16_t* __restrict__ Qb, const bf16_t* __restrict__ Kh, const bf16_t* __restrict__ Vh, int seq, char* lds,
;                                           int mode, float* scratch, float lam, float gscale, const float* __restrict__ subg, bf16_t* outp) {
;     ...
;     SBAR(); qkt(pA0, pA1, K_lds + bc * SHM_K, qr, r32, hi, m_reg);
;     finishSM(pB0, pB1, alB, l_reg, pa0, pa1, pa2, pa3); SBAR();
;     if (j + 3 < NT) SLOAD(SE, (j + 3) * KVBLK); SBAR();
;     pv_d0(o, vb0 + bp * SHM_V, pa0, pa1, pa2, pa3); partialSM(pA0, pA1, m_reg, alA, false);
.Lg1_rescback0:
	s_mov_b32 s21, 0
	s_lshl_b32 s59, s1, 14
	v_add_u32_e32 v172, s59, v177
	s_lshl_b32 s20, s2, 14
	s_add_i32 s20, s20, s79
	s_add_i32 s20, s20, s79
	s_add_i32 s58, s52, 4
	s_and_b32 s58, s58, 3
	s_lshl_b32 s58, s58, 13
	s_add_i32 s58, s58, s79
	s_add_i32 s58, s58, 0xc000
	s_waitcnt vmcnt(3)
	s_barrier
	s_mov_b32 m0, s20
	s_nop 0
	global_load_lds_dwordx4 v233, s[24:25]
	s_add_i32 m0, m0, 0x400
	s_nop 0
	global_load_lds_dwordx4 v234, s[24:25]
	s_mov_b32 m0, s58
	s_nop 0
	global_load_lds_dwordx4 v232, s[24:25]
	s_add_u32 s24, s24, 0x10000
	s_addc_u32 s25, s25, 0
	s_waitcnt lgkmcnt(7)
	v_mfma_f32_32x32x16_bf16 v[64:79], v[182:185], v[124:127], v[128:143]
	ds_read_b64_tr_b16 v[182:183], v172 offset:0x0
	ds_read_b64_tr_b16 v[184:185], v172 offset:0x800
	v_add_f32_e32 v159, v96, v97
	v_cvt_pk_bf16_f32 v96, v96, v97
	v_add_f32_e32 v160, v98, v99
	v_cvt_pk_bf16_f32 v97, v98, v99
	v_add_f32_e32 v159, v100, v159
	v_add_f32_e32 v160, v101, v160
	v_cvt_pk_bf16_f32 v98, v100, v101
	s_waitcnt lgkmcnt(8)
	v_mfma_f32_32x32x16_bf16 v[80:95], v[186:189], v[124:127], v[128:143]
	ds_read_b64_tr_b16 v[186:187], v172 offset:0x1000
	ds_read_b64_tr_b16 v[188:189], v172 offset:0x1800
	v_add_f32_e32 v159, v102, v159
	v_add_f32_e32 v160, v103, v160
	v_cvt_pk_bf16_f32 v99, v102, v103
	v_add_f32_e32 v159, v104, v159
	v_add_f32_e32 v160, v105, v160
	v_cvt_pk_bf16_f32 v100, v104, v105
	v_add_f32_e32 v159, v106, v159
	s_waitcnt lgkmcnt(9)
	v_mfma_f32_32x32x16_bf16 v[64:79], v[190:193], v[120:123], v[64:79]
	ds_read_b64_tr_b16 v[190:191], v172 offset:0x2000
	ds_read_b64_tr_b16 v[192:193], v172 offset:0x2800
	v_add_f32_e32 v160, v107, v160
	v_cvt_pk_bf16_f32 v101, v106, v107
	v_add_f32_e32 v159, v108, v159
	v_add_f32_e32 v160, v109, v160
	v_cvt_pk_bf16_f32 v102, v108, v109
	v_add_f32_e32 v159, v110, v159
	v_add_f32_e32 v160, v111, v160
	s_waitcnt lgkmcnt(10)
	v_mfma_f32_32x32x16_bf16 v[80:95], v[194:197], v[120:123], v[80:95]
	ds_read_b64_tr_b16 v[194:195], v172 offset:0x3000
	ds_read_b64_tr_b16 v[196:197], v172 offset:0x3800
	v_cvt_pk_bf16_f32 v103, v110, v111
	v_add_f32_e32 v159, v236, v159
	v_add_f32_e32 v160, v237, v160
	v_cvt_pk_bf16_f32 v104, v236, v237
	v_add_f32_e32 v159, v238, v159
	v_add_f32_e32 v160, v239, v160
	v_cvt_pk_bf16_f32 v105, v238, v239
	s_waitcnt lgkmcnt(11)
	v_mfma_f32_32x32x16_bf16 v[64:79], v[198:201], v[116:119], v[64:79]
	ds_read_b64_tr_b16 v[198:199], v172 offset:0x200
	ds_read_b64_tr_b16 v[200:201], v172 offset:0xa00
	v_add_f32_e32 v159, v240, v159
	v_add_f32_e32 v160, v241, v160
	v_cvt_pk_bf16_f32 v106, v240, v241
	v_add_f32_e32 v159, v242, v159
	v_add_f32_e32 v160, v243, v160
	v_cvt_pk_bf16_f32 v107, v242, v243
	v_add_f32_e32 v159, v244, v159
	s_waitcnt lgkmcnt(12)
	v_mfma_f32_32x32x16_bf16 v[80:95], v[202:205], v[116:119], v[80:95]
	ds_read_b64_tr_b16 v[202:203], v172 offset:0x1200
	ds_read_b64_tr_b16 v[204:205], v172 offset:0x1a00
	v_add_f32_e32 v160, v245, v160
	v_cvt_pk_bf16_f32 v108, v244, v245
	v_add_f32_e32 v159, v246, v159
	v_add_f32_e32 v160, v247, v160
	v_cvt_pk_bf16_f32 v109, v246, v247
	v_add_f32_e32 v159, v248, v159
	v_add_f32_e32 v160, v249, v160
	s_waitcnt lgkmcnt(13)
	v_mfma_f32_32x32x16_bf16 v[64:79], v[206:209], v[112:115], v[64:79]
	ds_read_b64_tr_b16 v[206:207], v172 offset:0x2200
	ds_read_b64_tr_b16 v[208:209], v172 offset:0x2a00
	v_cvt_pk_bf16_f32 v110, v248, v249
	v_add_f32_e32 v159, v250, v159
	v_add_f32_e32 v160, v251, v160
	v_cvt_pk_bf16_f32 v111, v250, v251
	v_add_f32_e32 v159, v159, v160
	v_fma_f32 v167, v167, v158, v159
	s_waitcnt lgkmcnt(14)
	v_mfma_f32_32x32x16_bf16 v[80:95], v[210:213], v[112:115], v[80:95]
	s_waitcnt lgkmcnt(12)
	v_mfma_f32_32x32x16_bf16 v[0:15], v[96:99], v[182:185], v[0:15]
	ds_read_b64_tr_b16 v[210:211], v172 offset:0x3200
	ds_read_b64_tr_b16 v[212:213], v172 offset:0x3a00
	v_max3_f32 v161, v64, v65, v66
	v_max3_f32 v161, v161, v67, v68
	v_max3_f32 v161, v161, v69, v70
	v_max3_f32 v161, v161, v71, v72
	s_waitcnt lgkmcnt(12)
	v_mfma_f32_32x32x16_bf16 v[0:15], v[100:103], v[186:189], v[0:15]
	ds_read_b64_tr_b16 v[182:183], v172 offset:0x400
	ds_read_b64_tr_b16 v[184:185], v172 offset:0xc00
	v_max3_f32 v161, v161, v73, v74
	v_max3_f32 v161, v161, v75, v76
	v_max3_f32 v161, v161, v77, v78
	v_max_f32_e32 v161, v161, v79
	s_waitcnt lgkmcnt(12)
	v_mfma_f32_32x32x16_bf16 v[0:15], v[104:107], v[190:193], v[0:15]
	ds_read_b64_tr_b16 v[186:187], v172 offset:0x1400
	ds_read_b64_tr_b16 v[188:189], v172 offset:0x1c00
	v_max3_f32 v216, v80, v81, v82
	v_max3_f32 v216, v216, v83, v84
	v_max3_f32 v216, v216, v85, v86
	v_max3_f32 v216, v216, v87, v88
	s_waitcnt lgkmcnt(12)
	v_mfma_f32_32x32x16_bf16 v[0:15], v[108:111], v[194:197], v[0:15]
	ds_read_b64_tr_b16 v[190:191], v172 offset:0x2400
	ds_read_b64_tr_b16 v[192:193], v172 offset:0x2c00
	v_max3_f32 v216, v216, v89, v90
	v_max3_f32 v216, v216, v91, v92
	v_max3_f32 v216, v216, v93, v94
	v_max_f32_e32 v216, v216, v95
	v_max_f32_e32 v161, v161, v216
	v_cmp_ge_f32_e32 vcc, s66, v161
	s_cmp_eq_u64 vcc, exec
	s_cbranch_scc0 .Lg1_rare1
	v_mov_b32_e32 v235, 1.0
